# prompt diff-attn loop: map-1 waves write the next K/V tile at the start of the half-step (skew against the SIMD partner); sample path cache loads coalesced per 128B line
# baseline (speedup 1.0000x reference)
;     ...
;     for (int tt = 0; tt < NT; tt += 2) {
;         if (tt + 2 < NT) DA_ISSUE(pfB, tt + 2);
;         DA_COMPUTE(tt, 0);
;         if (tt + 1 < NT) DA_WRITE(pfA, tt + 1, 1);
;         __syncthreads();
;         if (tt + 1 >= NT) break;
;         if (tt + 3 < NT) DA_ISSUE(pfA, tt + 3);
;         DA_COMPUTE(tt + 1, 1);
;         if (tt + 2 < NT) DA_WRITE(pfB, tt + 2, 0);
;         __syncthreads();
;     }
.LBB0_927:
	s_cmp_lg_u32 s9, 1
	s_cbranch_scc1 .Lp_e1_skip
	s_and_b64 vcc, exec, s[6:7]
	s_cbranch_vccz .Lp_e1w_all
	s_waitcnt vmcnt(4)
	s_branch .Lp_e1w_done

.Lp_e1w_done:
	ds_write_b128 v154, v[118:121] offset:38912
	ds_write_b128 v154, v[114:117] offset:38928
	ds_write_b128 v155, v[126:129] offset:57344
	ds_write_b128 v155, v[122:125] offset:57360

;     ...
;     for (int tt = 0; tt < NT; tt += 2) {
;         if (tt + 2 < NT) DA_ISSUE(pfB, tt + 2);
;         DA_COMPUTE(tt, 0);
;         if (tt + 1 < NT) DA_WRITE(pfA, tt + 1, 1);
.LBB0_931:
	s_cmp_lg_u32 s9, 0
	s_cbranch_scc1 .Lp_l1_skip
	s_and_b64 vcc, exec, s[6:7]
	s_cbranch_vccz .Lp_l1w_all
	s_waitcnt vmcnt(4)
	s_branch .Lp_l1w_done

;     ...
;         __syncthreads();
;         if (tt + 1 >= NT) break;
;         if (tt + 3 < NT) DA_ISSUE(pfA, tt + 3);
.Lp_l1_skip:
	s_cmp_ge_u32 s11, s13
	s_waitcnt lgkmcnt(0)
	s_barrier
	s_cselect_b32 s100, 1, 0
	s_cmp_lg_u32 s9, 1
	s_cbranch_scc1 .Lp_e2_skip
	s_and_b64 vcc, exec, s[6:7]
	s_cbranch_vccz .Lp_e2_skip
	s_waitcnt vmcnt(0)
	ds_write_b128 v154, v[134:137]
	ds_write_b128 v154, v[130:133] offset:16
	ds_write_b128 v155, v[142:145] offset:18432
	ds_write_b128 v155, v[138:141] offset:18448
.Lp_e2_skip:
	s_cmp_lg_u32 s100, 0
	s_cbranch_scc1 .LBB0_934
	v_ashrrev_i32_e32 v151, 31, v150
	v_lshlrev_b64 v[66:67], 10, v[150:151]
	v_lshl_or_b32 v66, v148, 1, v66
	v_lshl_add_u64 v[68:69], s[72:73], 0, v[66:67]
	v_lshl_add_u64 v[66:67], s[74:75], 0, v[66:67]
	global_load_dwordx4 v[114:117], v[68:69], off offset:16
	global_load_dwordx4 v[118:121], v[68:69], off
	global_load_dwordx4 v[122:125], v[66:67], off offset:16
	global_load_dwordx4 v[126:129], v[66:67], off
	s_add_i32 s28, s11, -2
	s_cmp_ge_u32 s28, s14
	s_cbranch_scc0 .LBB0_935

;     ...
;         DA_COMPUTE(tt + 1, 1);
;         if (tt + 2 < NT) DA_WRITE(pfB, tt + 2, 0);
;         __syncthreads();
.LBB0_938:
	s_cmp_lg_u32 s9, 0
	s_cbranch_scc1 .LBB0_924
	s_cmp_ge_u32 s11, s13
	s_cbranch_scc1 .Lp_w2_all
	s_waitcnt vmcnt(4)
	s_branch .Lp_w2_done

; #define GASP __attribute__((address_space(1)))
;     ...
;     const int S = SAMPLE ? PAST + DECS : SEQ, qpos0 = SAMPLE ? PAST : qi * 128 + sub * 32, rowq0 = SAMPLE ? NP + b * 32 : b * SEQ + qi * 128 + sub * 32;
;     const int NT = SAMPLE ? (PAST + DECS + 63) / 64 : 2 * qi + 2;
;     const int ntw = SAMPLE ? NT : min(NT, (qpos0 >> 6) + 1);
;     const float slope2 = exp2f(-2.f * (float)(h + 1)) * LOG2E;
;     bf16x8 qf[4];
;     { const bf16_t* qp = QB + (size_t)(rowq0 + r) * 512 + h * 128 + map * 64 + hi * 8;
; #pragma unroll
;       for (int d0 = 0; d0 < 4; ++d0) qf[d0] = *(const GASP bf16x8*)(qp + d0 * 16); }
;     f32x16 OT[NEB];
; #pragma unroll
;     for (int e = 0; e < NEB; ++e)
; #pragma unroll
;         for (int i = 0; i < 16; ++i) OT[e][i] = 0.f;
;     float m = -1e30f, l = 0.f;
;     const int lkey = tid >> 3, lc = tid & 7;
;     u32x4 pfA[NPF], pfB[SAMPLE ? 1 : NPF];
;     const float* ck = p.in[2]; const float* cv = p.in[3];
;     ...
;     const int i16 = lane & 15;
;     const int vlane_off = (4 * hi + (i16 >> 2)) * DA_VRS + (16 * ((lane >> 4) & 1) + 4 * (i16 & 3)) * 2;
;     const int tq = qpos0 + r;
;     ...
;     DA_ISSUE(pfA, 0); DA_WRITE(pfA, 0, 0);
;     if constexpr (SAMPLE) {
;         asm volatile("" : "+v"(qf[0]), "+v"(qf[1]), "+v"(qf[2]), "+v"(qf[3]));
;         __syncthreads();
; #pragma unroll 1
;         for (int tt = 0; tt < NT; ++tt) {
;             if (tt + 1 < NT) DA_ISSUE(pfA, tt + 1);
;             DA_COMPUTE(tt, tt & 1);
;             if (tt + 1 < NT) DA_WRITE(pfA, tt + 1, (tt + 1) & 1);
.LBB0_945:
	s_andn2_b64 vcc, exec, s[6:7]
	s_cbranch_vccnz .LBB0_869
	s_ashr_i32 s5, s4, 2
	v_mov_b32_e32 v0, v208
	s_lshl_b32 s56, s5, 5
	s_waitcnt vmcnt(4)
	v_ashrrev_i32_e32 v18, 3, v0
	s_lshl_b32 s41, s5, 12
	s_and_b32 s8, s4, 3
	v_and_b32_e32 v175, 31, v0
	s_add_i32 s4, s56, 0x8000
	v_add_u32_e32 v4, s41, v18
	v_or_b32_e32 v162, s4, v175
	s_lshl_b32 s4, s8, 7
	v_and_b32_e32 v8, 7, v0
	v_ashrrev_i32_e32 v5, 31, v4
	v_lshlrev_b64 v[4:5], 11, v[4:5]
	v_lshl_or_b32 v164, v8, 4, s4
	v_lshl_or_b32 v242, v8, 2, s4
	v_lshlrev_b32_e32 v243, 3, v8
	v_readfirstlane_b32 s33, v0
	v_ashrrev_i32_e32 v163, 31, v162
	v_lshl_or_b32 v4, v164, 2, v4
	s_ashr_i32 s40, s33, 8
	v_lshlrev_b64 v[2:3], 10, v[162:163]
	v_lshl_add_u64 v[6:7], s[24:25], 0, v[4:5]
	v_lshl_add_u64 v[4:5], s[26:27], 0, v[4:5]
	global_load_dwordx4 v[112:115], v[6:7], off offset:16
	global_load_dwordx4 v[116:119], v[6:7], off
	v_lshl_add_u64 v[2:3], s[70:71], 0, v[2:3]
	s_lshl_b32 s30, s8, 8
	global_load_dwordx4 v[120:123], v[6:7], off offset:48
	global_load_dwordx4 v[124:127], v[6:7], off offset:32
	global_load_dwordx4 v[128:131], v[4:5], off offset:16
	global_load_dwordx4 v[136:139], v[4:5], off
	s_lshl_b32 s6, s40, 6
	global_load_dwordx4 v[132:135], v[4:5], off offset:48
	global_load_dwordx4 v[140:143], v[4:5], off offset:32
	v_bfe_u32 v176, v0, 5, 1
	v_lshl_add_u64 v[2:3], v[2:3], 0, s[30:31]
	s_ashr_i32 s7, s6, 31
	v_lshl_add_u64 v[2:3], s[6:7], 1, v[2:3]
	v_lshlrev_b32_e32 v166, 4, v176
	v_mov_b32_e32 v167, v1
	v_lshl_add_u64 v[2:3], v[2:3], 0, v[166:167]
	global_load_dwordx4 v[144:147], v[2:3], off offset:96
	global_load_dwordx4 v[148:151], v[2:3], off offset:64
	global_load_dwordx4 v[152:155], v[2:3], off offset:32
	global_load_dwordx4 v[156:159], v[2:3], off
	s_not_b32 s5, s8
	v_lshrrev_b32_e32 v2, 2, v0
	v_and_b32_e32 v3, 16, v0
	v_lshlrev_b32_e32 v4, 2, v0
	v_bfe_u32 v5, v0, 2, 1
	v_lshlrev_b32_e32 v0, 5, v0
	s_movk_i32 s6, 0x2400
	s_lshl_b32 s5, s5, 1
	v_lshlrev_b32_e32 v167, 2, v176
	v_and_or_b32 v3, v4, 12, v3
	v_mad_u32_u24 v4, v5, s6, 0
	v_mul_lo_u32 v177, v18, s90
	v_and_b32_e32 v178, 0x60, v0
	v_ldexp_f32 v6, 1.0, s5
	v_mul_u32_u24_e32 v169, 0x2400, v5
	v_mul_lo_u32 v179, v18, s88
	v_lshlrev_b32_e32 v180, 5, v8
	v_and_or_b32 v0, v2, 3, v167
	v_lshlrev_b32_e32 v182, 1, v3
	v_add3_u32 v19, v4, v177, v178
	v_mul_f32_e32 v181, 0x3fb8aa3b, v6
	v_add3_u32 v20, 0, v179, v180
	v_mul_u32_u24_e32 v183, 0x140, v0
	v_readfirstlane_b32 s8, v181
	v_add_u32_e32 v186, 64, v18
	v_mov_b32_e32 v0, v1
	s_lshr_b32 s5, s33, 6
	s_bfe_u32 s30, s33, 0x20006
	s_lshl_b32 s98, s40, 1
	s_xor_b32 s30, s30, s98
	s_addk_i32 s56, 0x7000
	v_mul_u32_u24_e32 v184, 0x90, v175
	s_mov_b32 s9, s8
	s_mov_b32 s57, s8
	s_mov_b32 s84, s8
	s_mov_b32 s85, s8
	s_mov_b32 s86, s8
	s_mov_b32 s87, s8
	s_mov_b32 s91, s8
	s_mov_b32 s92, s8
	s_mov_b32 s93, s8
	s_mov_b32 s94, s8
	s_mov_b32 s95, s8
	s_mov_b32 s96, s8
	s_mov_b32 s97, s8
	s_mov_b32 s14, s8
	s_mov_b32 s15, s8
	v_sub_u32_e32 v185, v175, v167
	s_mov_b32 s34, 0
	v_mov_b32_e32 v168, 0xf149f2ca
	v_mov_b32_e32 v187, 0
	s_mov_b32 s28, 0
	s_waitcnt vmcnt(11)
	v_cvt_pk_bf16_f32 v4, v112, v113
	s_waitcnt vmcnt(10)
	v_cvt_pk_bf16_f32 v2, v116, v117
	v_cvt_pk_bf16_f32 v3, v118, v119
	v_cvt_pk_bf16_f32 v5, v114, v115
	s_waitcnt vmcnt(8)
	v_cvt_pk_bf16_f32 v6, v124, v125
	v_cvt_pk_bf16_f32 v7, v126, v127
	v_cvt_pk_bf16_f32 v8, v120, v121
	s_waitcnt vmcnt(4)
	v_cvt_pk_bf16_f32 v14, v140, v141
	v_cvt_pk_bf16_f32 v15, v142, v143
	v_cvt_pk_bf16_f32 v9, v122, v123
	v_cvt_pk_bf16_f32 v10, v136, v137
	v_cvt_pk_bf16_f32 v11, v138, v139
	v_cvt_pk_bf16_f32 v12, v128, v129
	v_cvt_pk_bf16_f32 v13, v130, v131
	v_cvt_pk_bf16_f32 v16, v132, v133
	v_cvt_pk_bf16_f32 v17, v134, v135
	ds_write_b128 v19, v[2:5]
	ds_write_b128 v19, v[6:9] offset:16
	ds_write_b128 v20, v[10:13] offset:18432
	ds_write_b128 v20, v[14:17] offset:18448
	v_mov_b32_e32 v14, v1
	v_mov_b32_e32 v15, v1
	v_mov_b32_e32 v2, v1
	v_mov_b32_e32 v3, v1
	v_mov_b32_e32 v4, v1
	v_mov_b32_e32 v5, v1
	v_mov_b32_e32 v6, v1
	v_mov_b32_e32 v7, v1
	v_mov_b32_e32 v8, v1
	v_mov_b32_e32 v9, v1
	v_mov_b32_e32 v10, v1
	v_mov_b32_e32 v11, v1
	v_mov_b32_e32 v12, v1
	v_mov_b32_e32 v13, v1
	v_mov_b64_e32 v[30:31], v[14:15]
	v_mov_b64_e32 v[46:47], v[14:15]
	v_mov_b64_e32 v[62:63], v[14:15]
	v_mov_b64_e32 v[78:79], v[14:15]
	v_mov_b64_e32 v[28:29], v[12:13]
	v_mov_b64_e32 v[26:27], v[10:11]
	v_mov_b64_e32 v[24:25], v[8:9]
	v_mov_b64_e32 v[22:23], v[6:7]
	v_mov_b64_e32 v[20:21], v[4:5]
	v_mov_b64_e32 v[18:19], v[2:3]
	v_mov_b64_e32 v[16:17], v[0:1]
	v_mov_b64_e32 v[44:45], v[12:13]
	v_mov_b64_e32 v[42:43], v[10:11]
	v_mov_b64_e32 v[40:41], v[8:9]
	v_mov_b64_e32 v[38:39], v[6:7]
	v_mov_b64_e32 v[36:37], v[4:5]
	v_mov_b64_e32 v[34:35], v[2:3]
	v_mov_b64_e32 v[32:33], v[0:1]
	v_mov_b64_e32 v[60:61], v[12:13]
	v_mov_b64_e32 v[58:59], v[10:11]
	v_mov_b64_e32 v[56:57], v[8:9]
	v_mov_b64_e32 v[54:55], v[6:7]
	v_mov_b64_e32 v[52:53], v[4:5]
	v_mov_b64_e32 v[50:51], v[2:3]
	v_mov_b64_e32 v[48:49], v[0:1]
	v_mov_b64_e32 v[76:77], v[12:13]
	v_mov_b64_e32 v[74:75], v[10:11]
	v_mov_b64_e32 v[72:73], v[8:9]
	v_mov_b64_e32 v[70:71], v[6:7]
	v_mov_b64_e32 v[68:69], v[4:5]
	v_mov_b64_e32 v[66:67], v[2:3]
	v_mov_b64_e32 v[64:65], v[0:1]
	s_waitcnt vmcnt(0)
	s_waitcnt lgkmcnt(0)
	s_barrier
	v_add_u32_e32 v2, s41, v186
	v_ashrrev_i32_e32 v3, 31, v2
	v_lshlrev_b64 v[2:3], 11, v[2:3]
	v_lshl_or_b32 v2, v242, 2, v2
	v_lshl_add_u64 v[4:5], s[24:25], 0, v[2:3]
	v_lshl_add_u64 v[2:3], s[26:27], 0, v[2:3]
	global_load_dwordx4 v[218:221], v[4:5], off offset:384
	global_load_dwordx4 v[222:225], v[4:5], off offset:256
	global_load_dwordx4 v[210:213], v[4:5], off offset:128
	global_load_dwordx4 v[214:217], v[4:5], off
	global_load_dwordx4 v[230:233], v[2:3], off offset:384
	global_load_dwordx4 v[238:241], v[2:3], off offset:256
	global_load_dwordx4 v[226:229], v[2:3], off offset:128
	global_load_dwordx4 v[234:237], v[2:3], off
	v_add_u32_e32 v186, 64, v186
.LBB0_947:
	s_cmpk_eq_i32 s34, 0xf000
	s_cselect_b64 s[6:7], -1, 0
	s_cmpk_lg_i32 s34, 0xf000
	s_cselect_b64 s[10:11], -1, 0
	s_cmp_gt_u32 s28, 62
	s_cbranch_scc1 .Ls2_issue_done
	s_bitcmp1_b32 s28, 0
	s_cbranch_scc1 .Ls2_issue_odd
	s_cmp_eq_u32 s28, 62
	s_cbranch_scc1 .Ls2_issue_bf16
	v_add_u32_e32 v2, s41, v186
	v_ashrrev_i32_e32 v3, 31, v2
	v_lshlrev_b64 v[2:3], 11, v[2:3]
	v_lshl_or_b32 v2, v242, 2, v2
	v_lshl_add_u64 v[4:5], s[24:25], 0, v[2:3]
	v_lshl_add_u64 v[2:3], s[26:27], 0, v[2:3]
	global_load_dwordx4 v[120:123], v[4:5], off offset:384
	global_load_dwordx4 v[124:127], v[4:5], off offset:256
	global_load_dwordx4 v[112:115], v[4:5], off offset:128
	global_load_dwordx4 v[116:119], v[4:5], off
	global_load_dwordx4 v[132:135], v[2:3], off offset:384
	global_load_dwordx4 v[140:143], v[2:3], off offset:256
	global_load_dwordx4 v[128:131], v[2:3], off offset:128
	global_load_dwordx4 v[136:139], v[2:3], off
	s_branch .Ls2_issue_done

.Ls2_issue_odd:
	v_add_u32_e32 v2, s41, v186
	v_ashrrev_i32_e32 v3, 31, v2
	v_lshlrev_b64 v[2:3], 11, v[2:3]
	v_lshl_or_b32 v2, v242, 2, v2
	v_lshl_add_u64 v[4:5], s[24:25], 0, v[2:3]
	v_lshl_add_u64 v[2:3], s[26:27], 0, v[2:3]
	global_load_dwordx4 v[218:221], v[4:5], off offset:384
	global_load_dwordx4 v[222:225], v[4:5], off offset:256
	global_load_dwordx4 v[210:213], v[4:5], off offset:128
	global_load_dwordx4 v[214:217], v[4:5], off
	global_load_dwordx4 v[230:233], v[2:3], off offset:384
	global_load_dwordx4 v[238:241], v[2:3], off offset:256
	global_load_dwordx4 v[226:229], v[2:3], off offset:128
	global_load_dwordx4 v[234:237], v[2:3], off

.Ls2_w_e:
	v_cvt_pk_bf16_f32 v2, v214, v215
	v_cvt_pk_bf16_f32 v3, v216, v217
	v_cvt_pk_bf16_f32 v4, v210, v211
	v_cvt_pk_bf16_f32 v5, v212, v213
	v_cvt_pk_bf16_f32 v6, v222, v223
	v_cvt_pk_bf16_f32 v7, v224, v225
	v_cvt_pk_bf16_f32 v8, v218, v219
	v_cvt_pk_bf16_f32 v9, v220, v221
	v_cvt_pk_bf16_f32 v10, v234, v235
	v_cvt_pk_bf16_f32 v11, v236, v237
	v_cvt_pk_bf16_f32 v12, v226, v227
	v_cvt_pk_bf16_f32 v13, v228, v229
	v_cvt_pk_bf16_f32 v80, v238, v239
	v_cvt_pk_bf16_f32 v81, v240, v241
	v_cvt_pk_bf16_f32 v82, v230, v231
	v_cvt_pk_bf16_f32 v83, v232, v233
	s_bitcmp1_b32 s6, 0
	s_cselect_b32 s7, 0x9800, 0
	v_add3_u32 v0, s7, v177, v243
	v_add3_u32 v14, s7, v179, v243
	ds_write_b64 v0, v[2:3]
	ds_write_b64 v0, v[4:5] offset:64
	ds_write_b64 v0, v[6:7] offset:9216
	ds_write_b64 v0, v[8:9] offset:9280
	ds_write_b64 v14, v[10:11] offset:18432
	ds_write_b64 v14, v[12:13] offset:18496
	ds_write_b64 v14, v[80:81] offset:18560
	ds_write_b64 v14, v[82:83] offset:18624
	s_branch .LBB0_960
.Ls2_write_odd:
	s_cmp_eq_u32 s28, 63
	s_cbranch_scc1 .Ls2_w_o_bf16
	s_waitcnt vmcnt(8)
	v_cvt_pk_bf16_f32 v2, v116, v117
	v_cvt_pk_bf16_f32 v3, v118, v119
	v_cvt_pk_bf16_f32 v4, v112, v113
	v_cvt_pk_bf16_f32 v5, v114, v115
	v_cvt_pk_bf16_f32 v6, v124, v125
	v_cvt_pk_bf16_f32 v7, v126, v127
	v_cvt_pk_bf16_f32 v8, v120, v121
	v_cvt_pk_bf16_f32 v9, v122, v123
	v_cvt_pk_bf16_f32 v10, v136, v137
	v_cvt_pk_bf16_f32 v11, v138, v139
	v_cvt_pk_bf16_f32 v12, v128, v129
	v_cvt_pk_bf16_f32 v13, v130, v131
	v_cvt_pk_bf16_f32 v80, v140, v141
	v_cvt_pk_bf16_f32 v81, v142, v143
	v_cvt_pk_bf16_f32 v82, v132, v133
	v_cvt_pk_bf16_f32 v83, v134, v135
	s_bitcmp1_b32 s6, 0
	s_cselect_b32 s7, 0x9800, 0
	v_add3_u32 v0, s7, v177, v243
	v_add3_u32 v14, s7, v179, v243
	ds_write_b64 v0, v[2:3]
	ds_write_b64 v0, v[4:5] offset:64
	ds_write_b64 v0, v[6:7] offset:9216
	ds_write_b64 v0, v[8:9] offset:9280
	ds_write_b64 v14, v[10:11] offset:18432
	ds_write_b64 v14, v[12:13] offset:18496
	ds_write_b64 v14, v[80:81] offset:18560
	ds_write_b64 v14, v[82:83] offset:18624
	s_branch .LBB0_960
